# LayerNorm wave_sum: first four butterfly steps (xor 1,2,4,8) done with DPP adds instead of ds_bpermute round trips; same values
# speedup vs baseline: 1.0006x; 1.0006x over previous
; __device__ __forceinline__ float wave_sum(float v) {
; #pragma unroll
;     for (int o = 1; o < 64; o <<= 1) v += __shfl_xor(v, o);
;     return v;
; __device__ __forceinline__ void ln_phase(const float* XF, float* dst, bf16_t* XB, const float* g, const float* bt, const float* srcs, const float* PART, int npart, bool wf32, int gw, int ngw, int lane) {
;     ...
;             float s = 0.f;
; #pragma unroll
;             for (int q = 0; q < 4; ++q) s += (v[h][q][0] + v[h][q][1]) + (v[h][q][2] + v[h][q][3]);
;             const float mean = wave_sum(s) * (1.f / DM); float s2 = 0.f;
; #pragma unroll
;             for (int q = 0; q < 4; ++q) { v[h][q] = v[h][q] - mean; s2 += (v[h][q][0] * v[h][q][0] + v[h][q][1] * v[h][q][1]) + (v[h][q][2] * v[h][q][2] + v[h][q][3] * v[h][q][3]); }
;             const float rstd = 1.f / sqrtf(wave_sum(s2) * (1.f / DM) + LN_EPS);
.LBB0_518:
	v_mov_b32_e32 v68, v67
	v_mov_b32_e32 v69, v32
	v_mov_b32_e32 v72, v66
	v_mov_b32_e32 v73, v33
	v_pk_add_f32 v[68:69], v[68:69], v[72:73]
	v_mov_b32_e32 v72, v61
	v_mov_b32_e32 v73, v62
	v_mov_b32_e32 v74, v60
	v_mov_b32_e32 v75, v63
	v_pk_add_f32 v[72:73], v[72:73], v[74:75]
	v_add_f32_e32 v68, v68, v69
	v_pk_add_f32 v[72:73], v[72:73], v[72:73] op_sel_hi:[0,1]
	v_add_f32_e32 v69, 0, v68
	v_add_f32_e32 v75, v58, v59
	v_add_f32_e32 v77, v34, v35
	v_mov_b32_e32 v74, v64
	v_mov_b32_e32 v76, v65
	v_mov_b32_e32 v72, v70
	v_mov_b32_e32 v68, v71
	v_pk_add_f32 v[74:75], v[74:75], v[76:77]
	v_pk_add_f32 v[68:69], v[72:73], v[68:69]
	s_nop 0
	v_pk_add_f32 v[68:69], v[74:75], v[68:69]
	s_nop 0
	v_add_f32_e32 v68, v68, v69
	s_nop 1
	v_add_f32_dpp v68, v68, v68 quad_perm:[1,0,3,2] row_mask:0xf bank_mask:0xf
	s_nop 1
	v_add_f32_dpp v68, v68, v68 quad_perm:[2,3,0,1] row_mask:0xf bank_mask:0xf
	s_nop 1
	v_add_f32_dpp v68, v68, v68 row_half_mirror row_mask:0xf bank_mask:0xf
	s_nop 1
	v_add_f32_dpp v68, v68, v68 row_mirror row_mask:0xf bank_mask:0xf
	ds_bpermute_b32 v69, v82, v68
	s_waitcnt lgkmcnt(0)
	v_add_f32_e32 v68, v68, v69
	ds_bpermute_b32 v69, v83, v68
	s_waitcnt lgkmcnt(0)
	v_add_f32_e32 v86, v68, v69
	v_fmamk_f32 v75, v86, 0xba800000, v67
	v_fmamk_f32 v74, v86, 0xba800000, v66
	v_fmamk_f32 v33, v86, 0xba800000, v33
	v_fmac_f32_e32 v32, 0xba800000, v86
	v_fmamk_f32 v69, v86, 0xba800000, v63
	v_fmamk_f32 v68, v86, 0xba800000, v62
	v_pk_mul_f32 v[62:63], v[32:33], v[32:33]
	v_pk_mul_f32 v[66:67], v[74:75], v[74:75]
	v_fmamk_f32 v61, v86, 0xba800000, v61
	v_pk_mov_b32 v[72:73], v[66:67], v[62:63] op_sel:[1,0]
	v_mov_b32_e32 v67, v63
	v_pk_add_f32 v[62:63], v[72:73], v[66:67]
	v_fmac_f32_e32 v60, 0xba800000, v86
	v_pk_add_f32 v[72:73], v[62:63], v[62:63] op_sel_hi:[0,1]
	v_pk_mul_f32 v[62:63], v[68:69], v[68:69]
	v_pk_mul_f32 v[66:67], v[60:61], v[60:61]
	v_fmac_f32_e32 v58, 0xba800000, v86
	v_pk_mov_b32 v[76:77], v[66:67], v[62:63] op_sel:[1,0]
	v_mov_b32_e32 v67, v63
	v_pk_add_f32 v[62:63], v[76:77], v[66:67]
	v_fmamk_f32 v66, v86, 0xba800000, v34
	v_fmamk_f32 v59, v86, 0xba800000, v59
	v_mul_f32_e32 v34, v58, v58
	v_fmamk_f32 v67, v86, 0xba800000, v35
	v_pk_fma_f32 v[34:35], v[58:59], v[58:59], v[34:35] op_sel_hi:[1,1,0]
	v_pk_add_f32 v[76:77], v[62:63], v[62:63] op_sel_hi:[0,1]
	v_mul_f32_e32 v34, v66, v66
	v_pk_fma_f32 v[84:85], v[66:67], v[66:67], v[34:35] op_sel_hi:[1,1,0]
	v_fmamk_f32 v63, v86, 0xba800000, v71
	v_fmamk_f32 v62, v86, 0xba800000, v70
	v_fmamk_f32 v65, v86, 0xba800000, v65
	v_fmac_f32_e32 v64, 0xba800000, v86
	v_mul_f32_e32 v34, v64, v64
	v_mul_f32_e32 v84, v65, v65
	v_mul_f32_e32 v72, v62, v62
	v_mul_f32_e32 v76, v63, v63
	v_pk_add_f32 v[34:35], v[34:35], v[84:85]
	v_pk_add_f32 v[70:71], v[72:73], v[76:77]
	s_nop 0
	v_pk_add_f32 v[34:35], v[34:35], v[70:71]
	s_nop 0
	v_add_f32_e32 v34, v34, v35
	s_nop 1
	v_add_f32_dpp v34, v34, v34 quad_perm:[1,0,3,2] row_mask:0xf bank_mask:0xf
	s_nop 1
	v_add_f32_dpp v34, v34, v34 quad_perm:[2,3,0,1] row_mask:0xf bank_mask:0xf
	s_nop 1
	v_add_f32_dpp v34, v34, v34 row_half_mirror row_mask:0xf bank_mask:0xf
	s_nop 1
	v_add_f32_dpp v34, v34, v34 row_mirror row_mask:0xf bank_mask:0xf
	ds_bpermute_b32 v35, v82, v34
	s_waitcnt lgkmcnt(0)
	v_add_f32_e32 v34, v34, v35
	ds_bpermute_b32 v35, v83, v34
	s_waitcnt lgkmcnt(0)
	v_add_f32_e32 v34, v34, v35
	v_fmamk_f32 v34, v34, 0x3a800000, v187
	v_mul_f32_e32 v35, 0x4f800000, v34
	v_cmp_gt_f32_e32 vcc, s71, v34
	s_nop 1
	v_cndmask_b32_e32 v34, v34, v35, vcc
	v_sqrt_f32_e32 v35, v34
	s_nop 0
	v_add_u32_e32 v70, -1, v35
	v_add_u32_e32 v71, 1, v35
	v_fma_f32 v72, -v70, v35, v34
	v_fma_f32 v73, -v71, v35, v34
	v_cmp_ge_f32_e64 s[6:7], 0, v72
	s_nop 1
	v_cndmask_b32_e64 v35, v35, v70, s[6:7]
	v_cmp_lt_f32_e64 s[6:7], 0, v73
	s_nop 1
	v_cndmask_b32_e64 v35, v35, v71, s[6:7]
	v_mul_f32_e32 v70, 0x37800000, v35
	v_cndmask_b32_e32 v35, v35, v70, vcc
	v_cmp_class_f32_e32 vcc, v34, v188
	s_nop 1
	v_cndmask_b32_e32 v34, v35, v34, vcc
	v_div_scale_f32 v35, s[6:7], v34, v34, 1.0
	v_rcp_f32_e32 v70, v35
	s_nop 0
	v_fma_f32 v71, -v35, v70, 1.0
	v_fmac_f32_e32 v70, v71, v70
	v_div_scale_f32 v71, vcc, 1.0, v34, 1.0
	v_mul_f32_e32 v72, v71, v70
	v_fma_f32 v73, -v35, v72, v71
	v_fmac_f32_e32 v72, v73, v70
	v_fma_f32 v35, -v35, v72, v71
	v_div_fmas_f32 v35, v35, v70, v72
	v_div_fixup_f32 v72, v35, v34, 1.0
	v_pk_mul_f32 v[70:71], v[74:75], v[72:73] op_sel_hi:[1,0]
	v_pk_mul_f32 v[32:33], v[32:33], v[72:73] op_sel_hi:[1,0]
	s_andn2_b64 vcc, exec, s[10:11]
	v_pk_fma_f32 v[34:35], v[2:3], v[32:33], v[10:11]
	v_pk_fma_f32 v[32:33], v[0:1], v[70:71], v[8:9]
	v_cndmask_b32_e64 v70, 0, 1, s[10:11]
	v_cmp_ne_u32_e64 s[6:7], 1, v70
	v_lshl_add_u64 v[70:71], s[12:13], 0, v[42:43]
	s_cbranch_vccnz .LBB0_520
	v_add_co_u32_e32 v74, vcc, 0x1ae00000, v70
	s_nop 1
	v_addc_co_u32_e32 v75, vcc, 0, v71, vcc
	global_store_dwordx4 v[74:75], v[32:35], off

; __device__ __forceinline__ float wave_sum(float v) {
; #pragma unroll
;     for (int o = 1; o < 64; o <<= 1) v += __shfl_xor(v, o);
;     return v;
; __device__ __forceinline__ void ln_phase(const float* XF, float* dst, bf16_t* XB, const float* g, const float* bt, const float* srcs, const float* PART, int npart, bool wf32, int gw, int ngw, int lane) {
;     ...
;             float s = 0.f;
; #pragma unroll
;             for (int q = 0; q < 4; ++q) s += (v[h][q][0] + v[h][q][1]) + (v[h][q][2] + v[h][q][3]);
;             const float mean = wave_sum(s) * (1.f / DM); float s2 = 0.f;
; #pragma unroll
;             for (int q = 0; q < 4; ++q) { v[h][q] = v[h][q] - mean; s2 += (v[h][q][0] * v[h][q][0] + v[h][q][1] * v[h][q][1]) + (v[h][q][2] * v[h][q][2] + v[h][q][3] * v[h][q][3]); }
;             const float rstd = 1.f / sqrtf(wave_sum(s2) * (1.f / DM) + LN_EPS);
.LBB0_530:
	v_mov_b32_e32 v62, v35
	v_mov_b32_e32 v63, v32
	v_mov_b32_e32 v64, v34
	v_mov_b32_e32 v65, v33
	v_pk_add_f32 v[62:63], v[62:63], v[64:65]
	v_mov_b32_e32 v64, v57
	v_mov_b32_e32 v65, v58
	v_mov_b32_e32 v66, v56
	v_mov_b32_e32 v67, v59
	v_pk_add_f32 v[64:65], v[64:65], v[66:67]
	v_add_f32_e32 v62, v62, v63
	v_pk_add_f32 v[64:65], v[64:65], v[64:65] op_sel_hi:[0,1]
	v_add_f32_e32 v63, 0, v62
	v_add_f32_e32 v67, v54, v55
	v_add_f32_e32 v69, v52, v53
	v_mov_b32_e32 v66, v60
	v_mov_b32_e32 v68, v61
	v_mov_b32_e32 v64, v50
	v_mov_b32_e32 v62, v51
	v_pk_add_f32 v[66:67], v[66:67], v[68:69]
	v_pk_add_f32 v[62:63], v[64:65], v[62:63]
	s_nop 0
	v_pk_add_f32 v[62:63], v[66:67], v[62:63]
	s_nop 0
	v_add_f32_e32 v62, v62, v63
	s_nop 1
	v_add_f32_dpp v62, v62, v62 quad_perm:[1,0,3,2] row_mask:0xf bank_mask:0xf
	s_nop 1
	v_add_f32_dpp v62, v62, v62 quad_perm:[2,3,0,1] row_mask:0xf bank_mask:0xf
	s_nop 1
	v_add_f32_dpp v62, v62, v62 row_half_mirror row_mask:0xf bank_mask:0xf
	s_nop 1
	v_add_f32_dpp v62, v62, v62 row_mirror row_mask:0xf bank_mask:0xf
	ds_bpermute_b32 v63, v82, v62
	s_waitcnt lgkmcnt(0)
	v_add_f32_e32 v62, v62, v63
	ds_bpermute_b32 v63, v83, v62
	s_waitcnt lgkmcnt(0)
	v_add_f32_e32 v70, v62, v63
	v_fmamk_f32 v35, v70, 0xba800000, v35
	v_fmamk_f32 v34, v70, 0xba800000, v34
	v_fmamk_f32 v33, v70, 0xba800000, v33
	v_fmac_f32_e32 v32, 0xba800000, v70
	v_pk_mul_f32 v[62:63], v[32:33], v[32:33]
	v_pk_mul_f32 v[64:65], v[34:35], v[34:35]
	v_fmamk_f32 v59, v70, 0xba800000, v59
	v_pk_mov_b32 v[66:67], v[64:65], v[62:63] op_sel:[1,0]
	v_mov_b32_e32 v65, v63
	v_fmamk_f32 v58, v70, 0xba800000, v58
	v_fmamk_f32 v57, v70, 0xba800000, v57
	v_pk_add_f32 v[62:63], v[66:67], v[64:65]
	v_fmac_f32_e32 v56, 0xba800000, v70
	v_pk_add_f32 v[62:63], v[62:63], v[62:63] op_sel_hi:[0,1]
	v_pk_mul_f32 v[64:65], v[58:59], v[58:59]
	v_pk_mul_f32 v[66:67], v[56:57], v[56:57]
	v_fmac_f32_e32 v54, 0xba800000, v70
	v_pk_mov_b32 v[68:69], v[66:67], v[64:65] op_sel:[1,0]
	v_mov_b32_e32 v67, v65
	v_fmamk_f32 v52, v70, 0xba800000, v52
	v_fmamk_f32 v55, v70, 0xba800000, v55
	v_mul_f32_e32 v62, v54, v54
	v_pk_add_f32 v[64:65], v[68:69], v[66:67]
	v_fmamk_f32 v53, v70, 0xba800000, v53
	v_pk_fma_f32 v[66:67], v[54:55], v[54:55], v[62:63] op_sel_hi:[1,1,0]
	v_mul_f32_e32 v62, v52, v52
	v_pk_add_f32 v[64:65], v[64:65], v[64:65] op_sel_hi:[0,1]
	v_pk_fma_f32 v[68:69], v[52:53], v[52:53], v[62:63] op_sel_hi:[1,1,0]
	v_fmamk_f32 v51, v70, 0xba800000, v51
	v_fmamk_f32 v50, v70, 0xba800000, v50
	v_fmamk_f32 v61, v70, 0xba800000, v61
	v_fmac_f32_e32 v60, 0xba800000, v70
	v_mul_f32_e32 v66, v60, v60
	v_mul_f32_e32 v68, v61, v61
	v_mul_f32_e32 v62, v50, v50
	v_mul_f32_e32 v64, v51, v51
	v_pk_add_f32 v[66:67], v[66:67], v[68:69]
	v_pk_add_f32 v[62:63], v[62:63], v[64:65]
	s_nop 0
	v_pk_add_f32 v[62:63], v[66:67], v[62:63]
	s_nop 0
	v_add_f32_e32 v62, v62, v63
	s_nop 1
	v_add_f32_dpp v62, v62, v62 quad_perm:[1,0,3,2] row_mask:0xf bank_mask:0xf
	s_nop 1
	v_add_f32_dpp v62, v62, v62 quad_perm:[2,3,0,1] row_mask:0xf bank_mask:0xf
	s_nop 1
	v_add_f32_dpp v62, v62, v62 row_half_mirror row_mask:0xf bank_mask:0xf
	s_nop 1
	v_add_f32_dpp v62, v62, v62 row_mirror row_mask:0xf bank_mask:0xf
	ds_bpermute_b32 v63, v82, v62
	s_waitcnt lgkmcnt(0)
	v_add_f32_e32 v62, v62, v63
	ds_bpermute_b32 v63, v83, v62
	s_waitcnt lgkmcnt(0)
	v_add_f32_e32 v62, v62, v63
	v_fmamk_f32 v62, v62, 0x3a800000, v187
	v_mul_f32_e32 v63, 0x4f800000, v62
	v_cmp_gt_f32_e32 vcc, s71, v62
	s_nop 1
	v_cndmask_b32_e32 v62, v62, v63, vcc
	v_sqrt_f32_e32 v63, v62
	s_nop 0
	v_add_u32_e32 v64, -1, v63
	v_add_u32_e32 v65, 1, v63
	v_fma_f32 v66, -v64, v63, v62
	v_fma_f32 v67, -v65, v63, v62
	v_cmp_ge_f32_e64 s[6:7], 0, v66
	s_nop 1
	v_cndmask_b32_e64 v63, v63, v64, s[6:7]
	v_cmp_lt_f32_e64 s[6:7], 0, v67
	s_nop 1
	v_cndmask_b32_e64 v63, v63, v65, s[6:7]
	v_mul_f32_e32 v64, 0x37800000, v63
	v_cndmask_b32_e32 v63, v63, v64, vcc
	v_cmp_class_f32_e32 vcc, v62, v188
	s_nop 1
	v_cndmask_b32_e32 v62, v63, v62, vcc
	v_div_scale_f32 v63, s[6:7], v62, v62, 1.0
	v_rcp_f32_e32 v64, v63
	s_nop 0
	v_fma_f32 v65, -v63, v64, 1.0
	v_fmac_f32_e32 v64, v65, v64
	v_div_scale_f32 v65, vcc, 1.0, v62, 1.0
	v_mul_f32_e32 v66, v65, v64
	v_fma_f32 v67, -v63, v66, v65
	v_fmac_f32_e32 v66, v67, v64
	v_fma_f32 v63, -v63, v66, v65
	v_div_fmas_f32 v63, v63, v64, v66
	v_div_fixup_f32 v64, v63, v62, 1.0
	v_pk_mul_f32 v[62:63], v[34:35], v[64:65] op_sel_hi:[1,0]
	v_pk_mul_f32 v[32:33], v[32:33], v[64:65] op_sel_hi:[1,0]
	s_andn2_b64 vcc, exec, s[10:11]
	v_pk_fma_f32 v[34:35], v[2:3], v[32:33], v[10:11]
	v_pk_fma_f32 v[32:33], v[0:1], v[62:63], v[8:9]
	v_cndmask_b32_e64 v62, 0, 1, s[10:11]
	v_cmp_ne_u32_e64 s[6:7], 1, v62
	v_lshl_add_u64 v[62:63], s[12:13], 0, v[46:47]
	s_cbranch_vccnz .LBB0_532
	v_add_co_u32_e32 v66, vcc, 0x1ae00000, v62
	s_nop 1
	v_addc_co_u32_e32 v67, vcc, 0, v63, vcc
	global_store_dwordx4 v[66:67], v[32:35], off

; __device__ __forceinline__ float wave_sum(float v) {
; #pragma unroll
;     for (int o = 1; o < 64; o <<= 1) v += __shfl_xor(v, o);
;     return v;
; __device__ __forceinline__ void ln_phase(const float* XF, float* dst, bf16_t* XB, const float* g, const float* bt, const float* srcs, const float* PART, int npart, bool wf32, int gw, int ngw, int lane) {
;     ...
;             float s = 0.f;
; #pragma unroll
;             for (int q = 0; q < 4; ++q) s += (v[h][q][0] + v[h][q][1]) + (v[h][q][2] + v[h][q][3]);
;             const float mean = wave_sum(s) * (1.f / DM); float s2 = 0.f;
; #pragma unroll
;             for (int q = 0; q < 4; ++q) { v[h][q] = v[h][q] - mean; s2 += (v[h][q][0] * v[h][q][0] + v[h][q][1] * v[h][q][1]) + (v[h][q][2] * v[h][q][2] + v[h][q][3] * v[h][q][3]); }
;             const float rstd = 1.f / sqrtf(wave_sum(s2) * (1.f / DM) + LN_EPS);
.LBB0_826:
	v_mov_b32_e32 v32, v63
	v_mov_b32_e32 v33, v56
	v_mov_b32_e32 v66, v62
	v_mov_b32_e32 v67, v57
	v_pk_add_f32 v[32:33], v[32:33], v[66:67]
	v_mov_b32_e32 v66, v55
	v_mov_b32_e32 v67, v60
	v_mov_b32_e32 v68, v54
	v_mov_b32_e32 v69, v61
	v_pk_add_f32 v[66:67], v[66:67], v[68:69]
	v_add_f32_e32 v32, v32, v33
	v_pk_add_f32 v[66:67], v[66:67], v[66:67] op_sel_hi:[0,1]
	v_add_f32_e32 v33, 0, v32
	v_add_f32_e32 v69, v52, v53
	v_add_f32_e32 v71, v58, v59
	v_mov_b32_e32 v68, v64
	v_mov_b32_e32 v70, v65
	v_mov_b32_e32 v66, v34
	v_mov_b32_e32 v32, v35
	v_pk_add_f32 v[68:69], v[68:69], v[70:71]
	v_pk_add_f32 v[32:33], v[66:67], v[32:33]
	s_or_b64 s[18:19], s[8:9], s[18:19]
	v_pk_add_f32 v[32:33], v[68:69], v[32:33]
	s_nop 0
	v_add_f32_e32 v32, v32, v33
	s_nop 1
	v_add_f32_dpp v32, v32, v32 quad_perm:[1,0,3,2] row_mask:0xf bank_mask:0xf
	s_nop 1
	v_add_f32_dpp v32, v32, v32 quad_perm:[2,3,0,1] row_mask:0xf bank_mask:0xf
	s_nop 1
	v_add_f32_dpp v32, v32, v32 row_half_mirror row_mask:0xf bank_mask:0xf
	s_nop 1
	v_add_f32_dpp v32, v32, v32 row_mirror row_mask:0xf bank_mask:0xf
	ds_bpermute_b32 v33, v76, v32
	s_waitcnt lgkmcnt(0)
	v_add_f32_e32 v32, v32, v33
	ds_bpermute_b32 v33, v77, v32
	s_waitcnt lgkmcnt(0)
	v_add_f32_e32 v80, v32, v33
	v_fmamk_f32 v33, v80, 0xba800000, v63
	v_fmamk_f32 v32, v80, 0xba800000, v62
	v_fmamk_f32 v57, v80, 0xba800000, v57
	v_fmac_f32_e32 v56, 0xba800000, v80
	v_fmamk_f32 v63, v80, 0xba800000, v61
	v_fmamk_f32 v62, v80, 0xba800000, v60
	v_pk_mul_f32 v[60:61], v[56:57], v[56:57]
	v_pk_mul_f32 v[66:67], v[32:33], v[32:33]
	v_fmamk_f32 v55, v80, 0xba800000, v55
	v_pk_mov_b32 v[68:69], v[66:67], v[60:61] op_sel:[1,0]
	v_mov_b32_e32 v67, v61
	v_pk_add_f32 v[60:61], v[68:69], v[66:67]
	v_fmac_f32_e32 v54, 0xba800000, v80
	v_pk_add_f32 v[66:67], v[60:61], v[60:61] op_sel_hi:[0,1]
	v_pk_mul_f32 v[60:61], v[62:63], v[62:63]
	v_pk_mul_f32 v[68:69], v[54:55], v[54:55]
	v_fmac_f32_e32 v52, 0xba800000, v80
	v_pk_mov_b32 v[70:71], v[68:69], v[60:61] op_sel:[1,0]
	v_mov_b32_e32 v69, v61
	v_pk_add_f32 v[60:61], v[70:71], v[68:69]
	v_fmamk_f32 v53, v80, 0xba800000, v53
	v_pk_add_f32 v[68:69], v[60:61], v[60:61] op_sel_hi:[0,1]
	v_fmamk_f32 v60, v80, 0xba800000, v58
	v_mul_f32_e32 v58, v52, v52
	v_fmamk_f32 v61, v80, 0xba800000, v59
	v_pk_fma_f32 v[70:71], v[52:53], v[52:53], v[58:59] op_sel_hi:[1,1,0]
	v_mul_f32_e32 v58, v60, v60
	v_pk_fma_f32 v[78:79], v[60:61], v[60:61], v[58:59] op_sel_hi:[1,1,0]
	v_fmamk_f32 v59, v80, 0xba800000, v35
	v_fmamk_f32 v58, v80, 0xba800000, v34
	v_fmamk_f32 v65, v80, 0xba800000, v65
	v_fmac_f32_e32 v64, 0xba800000, v80
	v_mul_f32_e32 v70, v64, v64
	v_mul_f32_e32 v78, v65, v65
	v_mul_f32_e32 v66, v58, v58
	v_mul_f32_e32 v68, v59, v59
	v_pk_add_f32 v[34:35], v[70:71], v[78:79]
	v_pk_add_f32 v[66:67], v[66:67], v[68:69]
	s_nop 0
	v_pk_add_f32 v[34:35], v[34:35], v[66:67]
	s_nop 0
	v_add_f32_e32 v34, v34, v35
	s_nop 1
	v_add_f32_dpp v34, v34, v34 quad_perm:[1,0,3,2] row_mask:0xf bank_mask:0xf
	s_nop 1
	v_add_f32_dpp v34, v34, v34 quad_perm:[2,3,0,1] row_mask:0xf bank_mask:0xf
	s_nop 1
	v_add_f32_dpp v34, v34, v34 row_half_mirror row_mask:0xf bank_mask:0xf
	s_nop 1
	v_add_f32_dpp v34, v34, v34 row_mirror row_mask:0xf bank_mask:0xf
	ds_bpermute_b32 v35, v76, v34
	s_waitcnt lgkmcnt(0)
	v_add_f32_e32 v34, v34, v35
	ds_bpermute_b32 v35, v77, v34
	s_waitcnt lgkmcnt(0)
	v_add_f32_e32 v34, v34, v35
	v_fmamk_f32 v34, v34, 0x3a800000, v187
	v_mul_f32_e32 v35, 0x4f800000, v34
	v_cmp_gt_f32_e32 vcc, s71, v34
	s_nop 1
	v_cndmask_b32_e32 v34, v34, v35, vcc
	v_sqrt_f32_e32 v35, v34
	s_nop 0
	v_add_u32_e32 v66, -1, v35
	v_add_u32_e32 v67, 1, v35
	v_fma_f32 v68, -v66, v35, v34
	v_fma_f32 v69, -v67, v35, v34
	v_cmp_ge_f32_e64 s[4:5], 0, v68
	s_nop 1
	v_cndmask_b32_e64 v35, v35, v66, s[4:5]
	v_cmp_lt_f32_e64 s[4:5], 0, v69
	s_nop 1
	v_cndmask_b32_e64 v35, v35, v67, s[4:5]
	v_mul_f32_e32 v66, 0x37800000, v35
	v_cndmask_b32_e32 v35, v35, v66, vcc
	v_cmp_class_f32_e32 vcc, v34, v188
	s_nop 1
	v_cndmask_b32_e32 v34, v35, v34, vcc
	v_div_scale_f32 v35, s[4:5], v34, v34, 1.0
	v_rcp_f32_e32 v66, v35
	s_nop 0
	v_fma_f32 v67, -v35, v66, 1.0
	v_fmac_f32_e32 v66, v67, v66
	v_div_scale_f32 v67, vcc, 1.0, v34, 1.0
	v_mul_f32_e32 v68, v67, v66
	v_fma_f32 v69, -v35, v68, v67
	v_fmac_f32_e32 v68, v69, v66
	v_fma_f32 v35, -v35, v68, v67
	v_div_fmas_f32 v35, v35, v66, v68
	v_div_fixup_f32 v66, v35, v34, 1.0
	v_pk_mul_f32 v[32:33], v[32:33], v[66:67] op_sel_hi:[1,0]
	v_pk_mul_f32 v[34:35], v[56:57], v[66:67] op_sel_hi:[1,0]
	v_cndmask_b32_e64 v56, 0, 1, s[18:19]
	v_pk_fma_f32 v[34:35], v[2:3], v[34:35], v[10:11]
	v_pk_fma_f32 v[32:33], v[0:1], v[32:33], v[8:9]
	v_cmp_ne_u32_e64 s[4:5], 1, v56
	s_andn2_b64 vcc, exec, s[18:19]
	v_lshl_add_u64 v[56:57], v[42:43], 0, s[10:11]
	s_cbranch_vccnz .LBB0_828
	global_store_dwordx4 v[56:57], v[32:35], off

; __device__ __forceinline__ float wave_sum(float v) {
; #pragma unroll
;     for (int o = 1; o < 64; o <<= 1) v += __shfl_xor(v, o);
;     return v;
; __device__ __forceinline__ void ln_phase(const float* XF, float* dst, bf16_t* XB, const float* g, const float* bt, const float* srcs, const float* PART, int npart, bool wf32, int gw, int ngw, int lane) {
;     ...
;             float s = 0.f;
; #pragma unroll
;             for (int q = 0; q < 4; ++q) s += (v[h][q][0] + v[h][q][1]) + (v[h][q][2] + v[h][q][3]);
;             const float mean = wave_sum(s) * (1.f / DM); float s2 = 0.f;
; #pragma unroll
;             for (int q = 0; q < 4; ++q) { v[h][q] = v[h][q] - mean; s2 += (v[h][q][0] * v[h][q][0] + v[h][q][1] * v[h][q][1]) + (v[h][q][2] * v[h][q][2] + v[h][q][3] * v[h][q][3]); }
;             const float rstd = 1.f / sqrtf(wave_sum(s2) * (1.f / DM) + LN_EPS);
.LBB0_838:
	v_mov_b32_e32 v32, v55
	v_mov_b32_e32 v33, v52
	v_mov_b32_e32 v44, v54
	v_mov_b32_e32 v45, v53
	v_pk_add_f32 v[32:33], v[32:33], v[44:45]
	v_mov_b32_e32 v44, v51
	v_mov_b32_e32 v45, v56
	v_mov_b32_e32 v60, v50
	v_mov_b32_e32 v61, v57
	v_pk_add_f32 v[44:45], v[44:45], v[60:61]
	v_add_f32_e32 v32, v32, v33
	v_pk_add_f32 v[44:45], v[44:45], v[44:45] op_sel_hi:[0,1]
	v_add_f32_e32 v33, 0, v32
	v_add_f32_e32 v61, v48, v49
	v_add_f32_e32 v63, v46, v47
	v_mov_b32_e32 v60, v58
	v_mov_b32_e32 v62, v59
	v_mov_b32_e32 v44, v34
	v_mov_b32_e32 v32, v35
	v_pk_add_f32 v[60:61], v[60:61], v[62:63]
	v_pk_add_f32 v[32:33], v[44:45], v[32:33]
	s_or_b64 s[16:17], s[8:9], s[18:19]
	v_pk_add_f32 v[32:33], v[60:61], v[32:33]
	s_nop 0
	v_add_f32_e32 v32, v32, v33
	s_nop 1
	v_add_f32_dpp v32, v32, v32 quad_perm:[1,0,3,2] row_mask:0xf bank_mask:0xf
	s_nop 1
	v_add_f32_dpp v32, v32, v32 quad_perm:[2,3,0,1] row_mask:0xf bank_mask:0xf
	s_nop 1
	v_add_f32_dpp v32, v32, v32 row_half_mirror row_mask:0xf bank_mask:0xf
	s_nop 1
	v_add_f32_dpp v32, v32, v32 row_mirror row_mask:0xf bank_mask:0xf
	ds_bpermute_b32 v33, v76, v32
	s_waitcnt lgkmcnt(0)
	v_add_f32_e32 v32, v32, v33
	ds_bpermute_b32 v33, v77, v32
	s_waitcnt lgkmcnt(0)
	v_add_f32_e32 v66, v32, v33
	v_fmamk_f32 v33, v66, 0xba800000, v55
	v_fmamk_f32 v32, v66, 0xba800000, v54
	v_fmamk_f32 v53, v66, 0xba800000, v53
	v_fmac_f32_e32 v52, 0xba800000, v66
	v_fmamk_f32 v55, v66, 0xba800000, v57
	v_fmamk_f32 v54, v66, 0xba800000, v56
	v_pk_mul_f32 v[44:45], v[52:53], v[52:53]
	v_pk_mul_f32 v[56:57], v[32:33], v[32:33]
	v_fmamk_f32 v51, v66, 0xba800000, v51
	v_pk_mov_b32 v[60:61], v[56:57], v[44:45] op_sel:[1,0]
	v_mov_b32_e32 v57, v45
	v_pk_add_f32 v[44:45], v[60:61], v[56:57]
	v_fmac_f32_e32 v50, 0xba800000, v66
	v_pk_add_f32 v[56:57], v[44:45], v[44:45] op_sel_hi:[0,1]
	v_pk_mul_f32 v[44:45], v[54:55], v[54:55]
	v_pk_mul_f32 v[60:61], v[50:51], v[50:51]
	v_fmac_f32_e32 v48, 0xba800000, v66
	v_pk_mov_b32 v[62:63], v[60:61], v[44:45] op_sel:[1,0]
	v_mov_b32_e32 v61, v45
	v_pk_add_f32 v[44:45], v[62:63], v[60:61]
	v_fmamk_f32 v46, v66, 0xba800000, v46
	v_pk_add_f32 v[60:61], v[44:45], v[44:45] op_sel_hi:[0,1]
	v_fmamk_f32 v49, v66, 0xba800000, v49
	v_mul_f32_e32 v44, v48, v48
	v_fmamk_f32 v47, v66, 0xba800000, v47
	v_pk_fma_f32 v[62:63], v[48:49], v[48:49], v[44:45] op_sel_hi:[1,1,0]
	v_mul_f32_e32 v44, v46, v46
	v_pk_fma_f32 v[64:65], v[46:47], v[46:47], v[44:45] op_sel_hi:[1,1,0]
	v_fmamk_f32 v45, v66, 0xba800000, v35
	v_fmamk_f32 v44, v66, 0xba800000, v34
	v_fmamk_f32 v59, v66, 0xba800000, v59
	v_fmac_f32_e32 v58, 0xba800000, v66
	v_mul_f32_e32 v62, v58, v58
	v_mul_f32_e32 v64, v59, v59
	v_mul_f32_e32 v56, v44, v44
	v_mul_f32_e32 v60, v45, v45
	v_pk_add_f32 v[34:35], v[62:63], v[64:65]
	v_pk_add_f32 v[56:57], v[56:57], v[60:61]
	s_nop 0
	v_pk_add_f32 v[34:35], v[34:35], v[56:57]
	s_nop 0
	v_add_f32_e32 v34, v34, v35
	s_nop 1
	v_add_f32_dpp v34, v34, v34 quad_perm:[1,0,3,2] row_mask:0xf bank_mask:0xf
	s_nop 1
	v_add_f32_dpp v34, v34, v34 quad_perm:[2,3,0,1] row_mask:0xf bank_mask:0xf
	s_nop 1
	v_add_f32_dpp v34, v34, v34 row_half_mirror row_mask:0xf bank_mask:0xf
	s_nop 1
	v_add_f32_dpp v34, v34, v34 row_mirror row_mask:0xf bank_mask:0xf
	ds_bpermute_b32 v35, v76, v34
	s_waitcnt lgkmcnt(0)
	v_add_f32_e32 v34, v34, v35
	ds_bpermute_b32 v35, v77, v34
	s_waitcnt lgkmcnt(0)
	v_add_f32_e32 v34, v34, v35
	v_fmamk_f32 v34, v34, 0x3a800000, v187
	v_mul_f32_e32 v35, 0x4f800000, v34
	v_cmp_gt_f32_e32 vcc, s71, v34
	s_nop 1
	v_cndmask_b32_e32 v34, v34, v35, vcc
	v_sqrt_f32_e32 v35, v34
	s_nop 0
	v_add_u32_e32 v56, -1, v35
	v_add_u32_e32 v57, 1, v35
	v_fma_f32 v60, -v56, v35, v34
	v_fma_f32 v61, -v57, v35, v34
	v_cmp_ge_f32_e64 s[4:5], 0, v60
	s_nop 1
	v_cndmask_b32_e64 v35, v35, v56, s[4:5]
	v_cmp_lt_f32_e64 s[4:5], 0, v61
	s_nop 1
	v_cndmask_b32_e64 v35, v35, v57, s[4:5]
	v_mul_f32_e32 v56, 0x37800000, v35
	v_cndmask_b32_e32 v35, v35, v56, vcc
	v_cmp_class_f32_e32 vcc, v34, v188
	s_nop 1
	v_cndmask_b32_e32 v34, v35, v34, vcc
	v_div_scale_f32 v35, s[4:5], v34, v34, 1.0
	v_rcp_f32_e32 v56, v35
	s_nop 0
	v_fma_f32 v57, -v35, v56, 1.0
	v_fmac_f32_e32 v56, v57, v56
	v_div_scale_f32 v57, vcc, 1.0, v34, 1.0
	v_mul_f32_e32 v60, v57, v56
	v_fma_f32 v61, -v35, v60, v57
	v_fmac_f32_e32 v60, v61, v56
	v_fma_f32 v35, -v35, v60, v57
	v_div_fmas_f32 v35, v35, v56, v60
	v_div_fixup_f32 v56, v35, v34, 1.0
	v_pk_mul_f32 v[32:33], v[32:33], v[56:57] op_sel_hi:[1,0]
	v_pk_mul_f32 v[34:35], v[52:53], v[56:57] op_sel_hi:[1,0]
	v_cndmask_b32_e64 v52, 0, 1, s[16:17]
	v_pk_fma_f32 v[34:35], v[2:3], v[34:35], v[10:11]
	v_pk_fma_f32 v[32:33], v[0:1], v[32:33], v[8:9]
	v_cmp_ne_u32_e64 s[4:5], 1, v52
	s_andn2_b64 vcc, exec, s[16:17]
	v_lshl_add_u64 v[52:53], v[42:43], 0, s[14:15]
	s_cbranch_vccnz .LBB0_840
	global_store_dwordx4 v[52:53], v[32:35], off
